# c24 + DIFF workgroup-synchronous scheduled re-reference: besides the data trigger, all waves re-reference on tiles j with (j & (2^(h+1)-1))==0
# speedup vs baseline: 1.0046x; 1.0046x over previous
.LBB0_1421:
	s_and_b32 s18, s18, 0x3fffffc0
	s_lshl_b32 s18, s18, 2
	s_add_i32 s18, s18, 0
	v_lshlrev_b32_e32 v2, 4, v39
	s_add_i32 s18, s18, 0x12300
	v_lshlrev_b32_e32 v1, 3, v39
	v_and_b32_e32 v2, 0xc0, v2
	v_lshlrev_b32_e32 v39, 1, v39
	v_and_or_b32 v2, v1, 24, v2
	v_and_b32_e32 v39, 32, v39
	v_and_b32_e32 v1, 0x100, v1
	s_cmp_lg_u32 0, -1
	v_or3_b32 v1, v2, v39, v1
	s_cselect_b32 s31, 0, 0
	v_add_u32_e32 v215, s31, v1
	v_max_f32_e32 v1, v5, v5
	v_max_f32_e32 v2, v4, v4
	v_max_f32_e32 v1, v2, v1
	v_max3_f32 v1, v1, v6, v7
	v_max3_f32 v1, v1, v8, v9
	v_max3_f32 v1, v1, v10, v11
	v_max3_f32 v1, v1, v12, v13
	v_max3_f32 v1, v1, v14, v15
	v_max3_f32 v1, v1, v16, v17
	v_max3_f32 v1, v1, v18, v19
	v_max3_f32 v1, v1, v20, v21
	v_max3_f32 v1, v1, v22, v23
	v_max3_f32 v1, v1, v24, v25
	v_max3_f32 v1, v1, v26, v27
	v_max3_f32 v1, v1, v28, v29
	v_max3_f32 v1, v1, v30, v31
	v_max3_f32 v1, v1, v32, v33
	v_max3_f32 v1, v1, v34, v35
	v_mov_b32_e32 v2, v1
	s_nop 1
	v_permlane32_swap_b32_e32 v1, v2
	v_max_f32_e32 v2, v2, v2
	v_max_f32_e32 v1, v1, v1
	v_max_f32_e32 v1, v1, v2
	s_ashr_i32 s31, s19, 31
	v_add_f32_e32 v221, 0, v1
	v_sub_f32_e32 v2, v4, v1
	v_sub_f32_e32 v4, v20, v1
	v_sub_f32_e32 v5, v5, v1
	v_sub_f32_e32 v20, v21, v1
	v_sub_f32_e32 v6, v6, v1
	v_sub_f32_e32 v21, v22, v1
	v_sub_f32_e32 v7, v7, v1
	v_sub_f32_e32 v22, v23, v1
	v_sub_f32_e32 v8, v8, v1
	v_sub_f32_e32 v23, v24, v1
	v_sub_f32_e32 v9, v9, v1
	v_sub_f32_e32 v24, v25, v1
	v_sub_f32_e32 v10, v10, v1
	v_sub_f32_e32 v25, v26, v1
	v_sub_f32_e32 v11, v11, v1
	v_sub_f32_e32 v26, v27, v1
	v_sub_f32_e32 v12, v12, v1
	v_sub_f32_e32 v27, v28, v1
	v_sub_f32_e32 v13, v13, v1
	v_sub_f32_e32 v28, v29, v1
	v_sub_f32_e32 v14, v14, v1
	v_sub_f32_e32 v29, v30, v1
	v_sub_f32_e32 v15, v15, v1
	v_sub_f32_e32 v30, v31, v1
	v_sub_f32_e32 v16, v16, v1
	v_sub_f32_e32 v31, v32, v1
	v_sub_f32_e32 v17, v17, v1
	v_sub_f32_e32 v32, v33, v1
	v_sub_f32_e32 v18, v18, v1
	v_sub_f32_e32 v33, v34, v1
	v_sub_f32_e32 v19, v19, v1
	v_sub_f32_e32 v1, v35, v1
	s_lshr_b32 s31, s31, 26
	v_exp_f32_e32 v96, v2
	v_exp_f32_e32 v80, v4
	v_exp_f32_e32 v97, v5
	v_exp_f32_e32 v81, v20
	v_exp_f32_e32 v98, v6
	v_exp_f32_e32 v82, v21
	v_exp_f32_e32 v99, v7
	v_exp_f32_e32 v83, v22
	v_exp_f32_e32 v100, v8
	v_exp_f32_e32 v84, v23
	v_exp_f32_e32 v101, v9
	v_exp_f32_e32 v85, v24
	v_exp_f32_e32 v102, v10
	v_exp_f32_e32 v86, v25
	v_exp_f32_e32 v103, v11
	v_exp_f32_e32 v87, v26
	v_exp_f32_e32 v104, v12
	v_exp_f32_e32 v88, v27
	v_exp_f32_e32 v105, v13
	v_exp_f32_e32 v89, v28
	v_exp_f32_e32 v106, v14
	v_exp_f32_e32 v90, v29
	v_exp_f32_e32 v107, v15
	v_exp_f32_e32 v91, v30
	v_exp_f32_e32 v108, v16
	v_exp_f32_e32 v92, v31
	v_exp_f32_e32 v109, v17
	v_exp_f32_e32 v93, v32
	v_exp_f32_e32 v110, v18
	v_exp_f32_e32 v94, v33
	v_exp_f32_e32 v111, v19
	v_exp_f32_e32 v95, v1
	s_add_i32 s19, s19, s31
	s_waitcnt vmcnt(0)
	v_mov_b32_e32 v14, v3
	v_mov_b32_e32 v15, v3
	s_ashr_i32 s31, s19, 6
	v_lshl_add_u64 v[190:191], s[34:35], 0, v[36:37]
	v_lshl_add_u32 v213, v38, 2, s18
	v_lshl_add_u32 v212, v0, 2, s18
	v_lshl_add_u64 v[194:195], s[40:41], 0, v[36:37]
	v_mov_b32_e32 v0, v3
	v_mov_b32_e32 v1, v3
	v_mov_b32_e32 v2, v3
	v_mov_b32_e32 v4, v3
	v_mov_b32_e32 v5, v3
	v_mov_b32_e32 v6, v3
	v_mov_b32_e32 v7, v3
	v_mov_b32_e32 v8, v3
	v_mov_b32_e32 v9, v3
	v_mov_b32_e32 v10, v3
	v_mov_b32_e32 v11, v3
	v_mov_b32_e32 v12, v3
	v_mov_b32_e32 v13, v3
	v_mov_b64_e32 v[30:31], v[14:15]
	v_mov_b64_e32 v[46:47], v[14:15]
	v_mov_b64_e32 v[62:63], v[14:15]
	v_mov_b64_e32 v[78:79], v[14:15]
	s_mov_b32 s44, 2
	s_mov_b32 s45, 4
	s_mov_b32 s69, 1
	s_mov_b32 s54, 0
	s_sub_i32 s19, 0, s31
	s_sub_i32 s64, 2, s31
	v_mov_b32_e32 v214, 0
	v_mov_b32_e32 v222, 1.0
	s_movk_i32 s65, 0x80
	v_mov_b64_e32 v[28:29], v[12:13]
	v_mov_b64_e32 v[26:27], v[10:11]
	v_mov_b64_e32 v[24:25], v[8:9]
	v_mov_b64_e32 v[22:23], v[6:7]
	v_mov_b64_e32 v[20:21], v[4:5]
	v_mov_b64_e32 v[18:19], v[2:3]
	v_mov_b64_e32 v[16:17], v[0:1]
	v_mov_b64_e32 v[44:45], v[12:13]
	v_mov_b64_e32 v[42:43], v[10:11]
	v_mov_b64_e32 v[40:41], v[8:9]
	v_mov_b64_e32 v[38:39], v[6:7]
	v_mov_b64_e32 v[36:37], v[4:5]
	v_mov_b64_e32 v[34:35], v[2:3]
	v_mov_b64_e32 v[32:33], v[0:1]
	v_mov_b64_e32 v[60:61], v[12:13]
	v_mov_b64_e32 v[58:59], v[10:11]
	v_mov_b64_e32 v[56:57], v[8:9]
	v_mov_b64_e32 v[54:55], v[6:7]
	v_mov_b64_e32 v[52:53], v[4:5]
	v_mov_b64_e32 v[50:51], v[2:3]
	v_mov_b64_e32 v[48:49], v[0:1]
	v_mov_b64_e32 v[76:77], v[12:13]
	v_mov_b64_e32 v[74:75], v[10:11]
	v_mov_b64_e32 v[72:73], v[8:9]
	v_mov_b64_e32 v[70:71], v[6:7]
	v_mov_b64_e32 v[68:69], v[4:5]
	v_mov_b64_e32 v[66:67], v[2:3]
	v_mov_b64_e32 v[64:65], v[0:1]
	v_readlane_b32 s99, v244, 2
	s_nop 3
	s_bfe_u32 s99, s99, 0x30004
	s_lshl_b32 s99, 2, s99
	s_add_i32 s99, s99, -1
	s_waitcnt vmcnt(0)

.LBB0_1437:
	s_waitcnt vmcnt(0)
	s_add_i32 s54, s44, 1
	s_cmp_lg_u32 s44, 2
	s_cselect_b32 s67, s54, 0
	s_waitcnt vmcnt(0)
	s_barrier
	s_lshl_b32 s66, s67, 14
	s_add_i32 s54, s81, s66
	v_lshl_add_u64 v[4:5], v[190:191], 0, s[52:53]
	s_mov_b32 m0, s54
	s_add_i32 s52, s71, s82
	global_load_lds_dwordx4 v[4:5], off
	v_lshl_add_u64 v[4:5], v[4:5], 0, s[14:15]
	s_add_i32 m0, s54, 0x2000
	s_add_i32 s52, s52, s27
	global_load_lds_dwordx4 v[4:5], off
	s_add_i32 m0, s52, 0xc000
	s_cmp_ge_u32 s45, s2
	s_cselect_b64 s[52:53], -1, 0
	s_cmp_lt_u32 s45, s2
	s_cselect_b32 s54, s45, s3
	s_lshl_b32 s54, s54, 6
	v_mad_u64_u32 v[4:5], s[54:55], s54, v209, v[192:193]
	v_lshl_add_u64 v[4:5], v[4:5], 0, s[10:11]
	global_load_lds_dwordx4 v[4:5], off
	v_cvt_f32_u32_e32 v1, s65
	s_mul_i32 s54, s44, 0x2100
	s_add_i32 s54, s54, 0
	v_add_u32_e32 v166, s54, v220
	v_sub_f32_e32 v196, v1, v161
	v_add_u32_e32 v167, s54, v217
	v_fma_f32 v1, v210, v196, -v221
	ds_read_b128 v[4:7], v166 offset:49152
	ds_read_b128 v[8:11], v167 offset:49152
	v_cvt_pk_bf16_f32 v2, v1, v3
	v_lshlrev_b32_e32 v2, 16, v2
	v_sub_f32_e32 v1, v1, v2
	v_cvt_pk_bf16_f32 v12, v1, v3
	v_lshlrev_b32_e32 v12, 16, v12
	v_sub_f32_e32 v1, v1, v12
	v_cvt_pk_bf16_f32 v12, v2, v12
	v_cvt_pk_bf16_f32 v1, v1, v3
	s_nop 0
	v_cndmask_b32_e64 v2, 0, v1, s[4:5]
	v_cndmask_b32_e64 v1, 0, v12, s[4:5]
	s_nop 1
	v_mfma_f32_32x32x16_bf16 v[128:143], v[248:251], v[0:3], 0
	v_add_f32_e32 v226, v96, v97
	v_add_f32_e32 v226, v98, v226
	v_add_f32_e32 v226, v99, v226
	v_add_f32_e32 v226, v100, v226
	s_nop 0
	v_mfma_f32_32x32x16_bf16 v[112:127], v[252:255], v[0:3], 0
	v_add_f32_e32 v1, v101, v226
	v_add_f32_e32 v1, v102, v1
	s_waitcnt lgkmcnt(0)
	v_mfma_f32_32x32x16_bf16 v[128:143], v[8:11], v[156:159], v[128:143]
	v_add_f32_e32 v1, v103, v1
	v_add_f32_e32 v1, v104, v1
	v_add_f32_e32 v1, v105, v1
	v_add_f32_e32 v1, v106, v1
	v_add_f32_e32 v1, v107, v1
	v_add_f32_e32 v1, v108, v1
	v_add_f32_e32 v1, v109, v1
	v_mfma_f32_32x32x16_bf16 v[112:127], v[4:7], v[156:159], v[112:127]
	ds_read_b128 v[4:7], v166 offset:51264
	ds_read_b128 v[8:11], v167 offset:51264
	v_add_f32_e32 v1, v110, v1
	v_add_f32_e32 v1, v111, v1
	v_add_f32_e32 v1, v80, v1
	v_add_f32_e32 v1, v81, v1
	v_add_f32_e32 v1, v82, v1
	v_add_f32_e32 v1, v83, v1
	s_waitcnt lgkmcnt(0)
	v_mfma_f32_32x32x16_bf16 v[128:143], v[8:11], v[152:155], v[128:143]
	v_add_f32_e32 v1, v84, v1
	v_add_f32_e32 v1, v85, v1
	v_add_f32_e32 v1, v86, v1
	v_add_f32_e32 v1, v87, v1
	v_add_f32_e32 v1, v88, v1
	v_add_f32_e32 v1, v89, v1
	v_add_f32_e32 v1, v90, v1
	v_mfma_f32_32x32x16_bf16 v[112:127], v[4:7], v[152:155], v[112:127]
	ds_read_b128 v[4:7], v166 offset:53376
	ds_read_b128 v[8:11], v167 offset:53376
	v_add_f32_e32 v1, v91, v1
	v_add_f32_e32 v1, v92, v1
	v_add_f32_e32 v1, v93, v1
	v_add_f32_e32 v1, v94, v1
	v_add_f32_e32 v1, v95, v1
	v_mov_b32_e32 v2, v1
	s_waitcnt lgkmcnt(0)
	v_mfma_f32_32x32x16_bf16 v[128:143], v[8:11], v[148:151], v[128:143]
	v_permlane32_swap_b32_e32 v1, v2
	v_mfma_f32_32x32x16_bf16 v[112:127], v[4:7], v[148:151], v[112:127]
	ds_read_b128 v[4:7], v166 offset:55488
	ds_read_b128 v[8:11], v167 offset:55488
	v_cvt_pk_bf16_f32 v166, v96, v97
	v_cvt_pk_bf16_f32 v167, v98, v99
	v_cvt_pk_bf16_f32 v168, v100, v101
	v_cvt_pk_bf16_f32 v169, v102, v103
	v_cvt_pk_bf16_f32 v12, v104, v105
	v_cvt_pk_bf16_f32 v13, v106, v107
	s_waitcnt lgkmcnt(0)
	v_mfma_f32_32x32x16_bf16 v[128:143], v[8:11], v[144:147], v[128:143]
	v_cvt_pk_bf16_f32 v14, v108, v109
	v_cvt_pk_bf16_f32 v15, v110, v111
	v_cvt_pk_bf16_f32 v8, v80, v81
	v_cvt_pk_bf16_f32 v9, v82, v83
	v_cvt_pk_bf16_f32 v10, v84, v85
	v_cvt_pk_bf16_f32 v11, v86, v87
	v_mfma_f32_32x32x16_bf16 v[112:127], v[4:7], v[144:147], v[112:127]
	v_cvt_pk_bf16_f32 v4, v88, v89
	v_cvt_pk_bf16_f32 v5, v90, v91
	v_cvt_pk_bf16_f32 v6, v92, v93
	v_cvt_pk_bf16_f32 v7, v94, v95
	v_lshl_add_u32 v162, s69, 14, v215
	ds_read_b64_tr_b16 v[182:183], v162 offset:0
	ds_read_b64_tr_b16 v[184:185], v162 offset:0x800
	ds_read_b64_tr_b16 v[178:179], v162 offset:0x1000
	ds_read_b64_tr_b16 v[180:181], v162 offset:0x1800
	s_add_i32 s54, s64, s45
	ds_read_b64_tr_b16 v[174:175], v162 offset:0x2000
	s_cmp_eq_u32 s54, 4
	ds_read_b64_tr_b16 v[176:177], v162 offset:0x2800
	s_cselect_b64 s[54:55], -1, 0
	ds_read_b64_tr_b16 v[170:171], v162 offset:0x3000
	v_cndmask_b32_e64 v80, 0, 1, s[54:55]
	ds_read_b64_tr_b16 v[172:173], v162 offset:0x3800
	s_add_i32 s98, s70, 2
	s_cmp_le_i32 s98, s31
	s_cbranch_scc0 .Lold_even
	v_max3_f32 v245, v128, v129, v130
	v_max3_f32 v246, v112, v113, v114
	v_max3_f32 v245, v245, v131, v132
	v_max3_f32 v246, v246, v115, v116
	v_max3_f32 v245, v245, v133, v134
	v_max3_f32 v246, v246, v117, v118
	v_max3_f32 v245, v245, v135, v136
	v_max3_f32 v246, v246, v119, v120
	v_max3_f32 v245, v245, v137, v138
	v_max3_f32 v246, v246, v121, v122
	v_max3_f32 v245, v245, v139, v140
	v_max3_f32 v246, v246, v123, v124
	v_max3_f32 v245, v245, v141, v142
	v_max3_f32 v246, v246, v125, v126
	v_max_f32_e32 v245, v245, v143
	v_max_f32_e32 v246, v246, v127
	v_max_f32_e32 v245, v245, v246
	v_mov_b32_e32 v246, v245
	s_nop 1
	v_permlane32_swap_b32_e32 v245, v246
	v_max_f32_e32 v245, v245, v246
	v_cmp_ge_f32_e32 vcc, s68, v245
	s_cmp_eq_u64 vcc, exec
	v_mov_b32_e32 v196, 1.0
	s_cbranch_scc0 .Lf_even_resc
	s_add_i32 s98, s45, -2
	s_and_b32 s98, s98, s99
	s_cbranch_scc0 .Lf_even_resc
